# SwiGLU epilogue rewritten by hand: packed f32 scale/add/mul (v_pk_*), 8 independent exp/rcp per row, same op order per element
# speedup vs baseline: 1.0132x; 1.0132x over previous
.LBB0_577:
	s_mov_b32 s34, 0xbfb8aa3b
	s_mov_b32 s35, 0xbfb8aa3b
	v_lshl_or_b32 v146, s47, 7, v142
	v_lshl_add_u32 v144, s48, 8, v140
	v_ashrrev_i32_e32 v147, 31, v146
	v_mov_b64_e32 v[138:139], s[96:97]
	s_movk_i32 s23, 0x1600
	v_lshlrev_b64 v[148:149], 1, v[146:147]
	v_pk_mul_f32 v[160:161], v[124:125], s[34:35]
	v_pk_mul_f32 v[162:163], v[126:127], s[34:35]
	v_pk_mul_f32 v[164:165], v[120:121], s[34:35]
	v_pk_mul_f32 v[166:167], v[122:123], s[34:35]
	v_exp_f32_e32 v160, v160
	v_exp_f32_e32 v161, v161
	v_exp_f32_e32 v162, v162
	v_exp_f32_e32 v163, v163
	v_exp_f32_e32 v164, v164
	v_exp_f32_e32 v165, v165
	v_exp_f32_e32 v166, v166
	v_exp_f32_e32 v167, v167
	v_pk_add_f32 v[160:161], v[160:161], 1.0 op_sel_hi:[1,0]
	v_pk_add_f32 v[162:163], v[162:163], 1.0 op_sel_hi:[1,0]
	v_pk_add_f32 v[164:165], v[164:165], 1.0 op_sel_hi:[1,0]
	v_pk_add_f32 v[166:167], v[166:167], 1.0 op_sel_hi:[1,0]
	v_rcp_f32_e32 v160, v160
	v_rcp_f32_e32 v161, v161
	v_rcp_f32_e32 v162, v162
	v_rcp_f32_e32 v163, v163
	v_rcp_f32_e32 v164, v164
	v_rcp_f32_e32 v165, v165
	v_rcp_f32_e32 v166, v166
	v_rcp_f32_e32 v167, v167
	v_pk_mul_f32 v[124:125], v[124:125], v[160:161]
	v_pk_mul_f32 v[126:127], v[126:127], v[162:163]
	v_pk_mul_f32 v[120:121], v[120:121], v[164:165]
	v_pk_mul_f32 v[122:123], v[122:123], v[166:167]
	v_pk_mul_f32 v[116:117], v[124:125], v[116:117]
	v_pk_mul_f32 v[118:119], v[126:127], v[118:119]
	v_pk_mul_f32 v[112:113], v[120:121], v[112:113]
	v_pk_mul_f32 v[114:115], v[122:123], v[114:115]
	v_mad_i64_i32 v[150:151], s[30:31], v144, s23, v[138:139]
	v_cvt_pk_bf16_f32 v168, v116, v117
	v_cvt_pk_bf16_f32 v169, v118, v119
	v_cvt_pk_bf16_f32 v170, v112, v113
	v_cvt_pk_bf16_f32 v171, v114, v115
	v_lshl_add_u64 v[150:151], v[150:151], 0, v[148:149]
	global_store_dwordx4 v[150:151], v[168:171], off
	v_pk_mul_f32 v[160:161], v[108:109], s[34:35]
	v_pk_mul_f32 v[162:163], v[110:111], s[34:35]
	v_pk_mul_f32 v[164:165], v[104:105], s[34:35]
	v_pk_mul_f32 v[166:167], v[106:107], s[34:35]
	v_exp_f32_e32 v160, v160
	v_exp_f32_e32 v161, v161
	v_exp_f32_e32 v162, v162
	v_exp_f32_e32 v163, v163
	v_exp_f32_e32 v164, v164
	v_exp_f32_e32 v165, v165
	v_exp_f32_e32 v166, v166
	v_exp_f32_e32 v167, v167
	v_pk_add_f32 v[160:161], v[160:161], 1.0 op_sel_hi:[1,0]
	v_pk_add_f32 v[162:163], v[162:163], 1.0 op_sel_hi:[1,0]
	v_pk_add_f32 v[164:165], v[164:165], 1.0 op_sel_hi:[1,0]
	v_pk_add_f32 v[166:167], v[166:167], 1.0 op_sel_hi:[1,0]
	v_rcp_f32_e32 v160, v160
	v_rcp_f32_e32 v161, v161
	v_rcp_f32_e32 v162, v162
	v_rcp_f32_e32 v163, v163
	v_rcp_f32_e32 v164, v164
	v_rcp_f32_e32 v165, v165
	v_rcp_f32_e32 v166, v166
	v_rcp_f32_e32 v167, v167
	v_pk_mul_f32 v[108:109], v[108:109], v[160:161]
	v_pk_mul_f32 v[110:111], v[110:111], v[162:163]
	v_pk_mul_f32 v[104:105], v[104:105], v[164:165]
	v_pk_mul_f32 v[106:107], v[106:107], v[166:167]
	v_pk_mul_f32 v[100:101], v[108:109], v[100:101]
	v_pk_mul_f32 v[102:103], v[110:111], v[102:103]
	v_pk_mul_f32 v[96:97], v[104:105], v[96:97]
	v_pk_mul_f32 v[98:99], v[106:107], v[98:99]
	v_or_b32_e32 v152, 16, v144
	v_mad_i64_i32 v[154:155], s[30:31], v152, s23, v[138:139]
	v_cvt_pk_bf16_f32 v172, v100, v101
	v_cvt_pk_bf16_f32 v173, v102, v103
	v_cvt_pk_bf16_f32 v174, v96, v97
	v_cvt_pk_bf16_f32 v175, v98, v99
	v_lshl_add_u64 v[154:155], v[154:155], 0, v[148:149]
	global_store_dwordx4 v[154:155], v[172:175], off
	v_pk_mul_f32 v[160:161], v[92:93], s[34:35]
	v_pk_mul_f32 v[162:163], v[94:95], s[34:35]
	v_pk_mul_f32 v[164:165], v[88:89], s[34:35]
	v_pk_mul_f32 v[166:167], v[90:91], s[34:35]
	v_exp_f32_e32 v160, v160
	v_exp_f32_e32 v161, v161
	v_exp_f32_e32 v162, v162
	v_exp_f32_e32 v163, v163
	v_exp_f32_e32 v164, v164
	v_exp_f32_e32 v165, v165
	v_exp_f32_e32 v166, v166
	v_exp_f32_e32 v167, v167
	v_pk_add_f32 v[160:161], v[160:161], 1.0 op_sel_hi:[1,0]
	v_pk_add_f32 v[162:163], v[162:163], 1.0 op_sel_hi:[1,0]
	v_pk_add_f32 v[164:165], v[164:165], 1.0 op_sel_hi:[1,0]
	v_pk_add_f32 v[166:167], v[166:167], 1.0 op_sel_hi:[1,0]
	v_rcp_f32_e32 v160, v160
	v_rcp_f32_e32 v161, v161
	v_rcp_f32_e32 v162, v162
	v_rcp_f32_e32 v163, v163
	v_rcp_f32_e32 v164, v164
	v_rcp_f32_e32 v165, v165
	v_rcp_f32_e32 v166, v166
	v_rcp_f32_e32 v167, v167
	v_pk_mul_f32 v[92:93], v[92:93], v[160:161]
	v_pk_mul_f32 v[94:95], v[94:95], v[162:163]
	v_pk_mul_f32 v[88:89], v[88:89], v[164:165]
	v_pk_mul_f32 v[90:91], v[90:91], v[166:167]
	v_pk_mul_f32 v[84:85], v[92:93], v[84:85]
	v_pk_mul_f32 v[86:87], v[94:95], v[86:87]
	v_pk_mul_f32 v[80:81], v[88:89], v[80:81]
	v_pk_mul_f32 v[82:83], v[90:91], v[82:83]
	v_or_b32_e32 v152, 32, v144
	v_mad_i64_i32 v[150:151], s[30:31], v152, s23, v[138:139]
	v_cvt_pk_bf16_f32 v168, v84, v85
	v_cvt_pk_bf16_f32 v169, v86, v87
	v_cvt_pk_bf16_f32 v170, v80, v81
	v_cvt_pk_bf16_f32 v171, v82, v83
	v_lshl_add_u64 v[150:151], v[150:151], 0, v[148:149]
	global_store_dwordx4 v[150:151], v[168:171], off
	v_pk_mul_f32 v[160:161], v[76:77], s[34:35]
	v_pk_mul_f32 v[162:163], v[78:79], s[34:35]
	v_pk_mul_f32 v[164:165], v[72:73], s[34:35]
	v_pk_mul_f32 v[166:167], v[74:75], s[34:35]
	v_exp_f32_e32 v160, v160
	v_exp_f32_e32 v161, v161
	v_exp_f32_e32 v162, v162
	v_exp_f32_e32 v163, v163
	v_exp_f32_e32 v164, v164
	v_exp_f32_e32 v165, v165
	v_exp_f32_e32 v166, v166
	v_exp_f32_e32 v167, v167
	v_pk_add_f32 v[160:161], v[160:161], 1.0 op_sel_hi:[1,0]
	v_pk_add_f32 v[162:163], v[162:163], 1.0 op_sel_hi:[1,0]
	v_pk_add_f32 v[164:165], v[164:165], 1.0 op_sel_hi:[1,0]
	v_pk_add_f32 v[166:167], v[166:167], 1.0 op_sel_hi:[1,0]
	v_rcp_f32_e32 v160, v160
	v_rcp_f32_e32 v161, v161
	v_rcp_f32_e32 v162, v162
	v_rcp_f32_e32 v163, v163
	v_rcp_f32_e32 v164, v164
	v_rcp_f32_e32 v165, v165
	v_rcp_f32_e32 v166, v166
	v_rcp_f32_e32 v167, v167
	v_pk_mul_f32 v[76:77], v[76:77], v[160:161]
	v_pk_mul_f32 v[78:79], v[78:79], v[162:163]
	v_pk_mul_f32 v[72:73], v[72:73], v[164:165]
	v_pk_mul_f32 v[74:75], v[74:75], v[166:167]
	v_pk_mul_f32 v[68:69], v[76:77], v[68:69]
	v_pk_mul_f32 v[70:71], v[78:79], v[70:71]
	v_pk_mul_f32 v[64:65], v[72:73], v[64:65]
	v_pk_mul_f32 v[66:67], v[74:75], v[66:67]
	v_or_b32_e32 v152, 48, v144
	v_mad_i64_i32 v[154:155], s[30:31], v152, s23, v[138:139]
	v_cvt_pk_bf16_f32 v172, v68, v69
	v_cvt_pk_bf16_f32 v173, v70, v71
	v_cvt_pk_bf16_f32 v174, v64, v65
	v_cvt_pk_bf16_f32 v175, v66, v67
	v_lshl_add_u64 v[154:155], v[154:155], 0, v[148:149]
	global_store_dwordx4 v[154:155], v[172:175], off
	v_pk_mul_f32 v[160:161], v[60:61], s[34:35]
	v_pk_mul_f32 v[162:163], v[62:63], s[34:35]
	v_pk_mul_f32 v[164:165], v[56:57], s[34:35]
	v_pk_mul_f32 v[166:167], v[58:59], s[34:35]
	v_exp_f32_e32 v160, v160
	v_exp_f32_e32 v161, v161
	v_exp_f32_e32 v162, v162
	v_exp_f32_e32 v163, v163
	v_exp_f32_e32 v164, v164
	v_exp_f32_e32 v165, v165
	v_exp_f32_e32 v166, v166
	v_exp_f32_e32 v167, v167
	v_pk_add_f32 v[160:161], v[160:161], 1.0 op_sel_hi:[1,0]
	v_pk_add_f32 v[162:163], v[162:163], 1.0 op_sel_hi:[1,0]
	v_pk_add_f32 v[164:165], v[164:165], 1.0 op_sel_hi:[1,0]
	v_pk_add_f32 v[166:167], v[166:167], 1.0 op_sel_hi:[1,0]
	v_rcp_f32_e32 v160, v160
	v_rcp_f32_e32 v161, v161
	v_rcp_f32_e32 v162, v162
	v_rcp_f32_e32 v163, v163
	v_rcp_f32_e32 v164, v164
	v_rcp_f32_e32 v165, v165
	v_rcp_f32_e32 v166, v166
	v_rcp_f32_e32 v167, v167
	v_pk_mul_f32 v[60:61], v[60:61], v[160:161]
	v_pk_mul_f32 v[62:63], v[62:63], v[162:163]
	v_pk_mul_f32 v[56:57], v[56:57], v[164:165]
	v_pk_mul_f32 v[58:59], v[58:59], v[166:167]
	v_pk_mul_f32 v[52:53], v[60:61], v[52:53]
	v_pk_mul_f32 v[54:55], v[62:63], v[54:55]
	v_pk_mul_f32 v[48:49], v[56:57], v[48:49]
	v_pk_mul_f32 v[50:51], v[58:59], v[50:51]
	v_add_u32_e32 v152, 0x80, v144
	v_mad_i64_i32 v[150:151], s[30:31], v152, s23, v[138:139]
	v_cvt_pk_bf16_f32 v168, v52, v53
	v_cvt_pk_bf16_f32 v169, v54, v55
	v_cvt_pk_bf16_f32 v170, v48, v49
	v_cvt_pk_bf16_f32 v171, v50, v51
	v_lshl_add_u64 v[150:151], v[150:151], 0, v[148:149]
	global_store_dwordx4 v[150:151], v[168:171], off
	v_pk_mul_f32 v[160:161], v[44:45], s[34:35]
	v_pk_mul_f32 v[162:163], v[46:47], s[34:35]
	v_pk_mul_f32 v[164:165], v[40:41], s[34:35]
	v_pk_mul_f32 v[166:167], v[42:43], s[34:35]
	v_exp_f32_e32 v160, v160
	v_exp_f32_e32 v161, v161
	v_exp_f32_e32 v162, v162
	v_exp_f32_e32 v163, v163
	v_exp_f32_e32 v164, v164
	v_exp_f32_e32 v165, v165
	v_exp_f32_e32 v166, v166
	v_exp_f32_e32 v167, v167
	v_pk_add_f32 v[160:161], v[160:161], 1.0 op_sel_hi:[1,0]
	v_pk_add_f32 v[162:163], v[162:163], 1.0 op_sel_hi:[1,0]
	v_pk_add_f32 v[164:165], v[164:165], 1.0 op_sel_hi:[1,0]
	v_pk_add_f32 v[166:167], v[166:167], 1.0 op_sel_hi:[1,0]
	v_rcp_f32_e32 v160, v160
	v_rcp_f32_e32 v161, v161
	v_rcp_f32_e32 v162, v162
	v_rcp_f32_e32 v163, v163
	v_rcp_f32_e32 v164, v164
	v_rcp_f32_e32 v165, v165
	v_rcp_f32_e32 v166, v166
	v_rcp_f32_e32 v167, v167
	v_pk_mul_f32 v[44:45], v[44:45], v[160:161]
	v_pk_mul_f32 v[46:47], v[46:47], v[162:163]
	v_pk_mul_f32 v[40:41], v[40:41], v[164:165]
	v_pk_mul_f32 v[42:43], v[42:43], v[166:167]
	v_pk_mul_f32 v[36:37], v[44:45], v[36:37]
	v_pk_mul_f32 v[38:39], v[46:47], v[38:39]
	v_pk_mul_f32 v[32:33], v[40:41], v[32:33]
	v_pk_mul_f32 v[34:35], v[42:43], v[34:35]
	v_add_u32_e32 v152, 0x90, v144
	v_mad_i64_i32 v[154:155], s[30:31], v152, s23, v[138:139]
	v_cvt_pk_bf16_f32 v172, v36, v37
	v_cvt_pk_bf16_f32 v173, v38, v39
	v_cvt_pk_bf16_f32 v174, v32, v33
	v_cvt_pk_bf16_f32 v175, v34, v35
	v_lshl_add_u64 v[154:155], v[154:155], 0, v[148:149]
	global_store_dwordx4 v[154:155], v[172:175], off
	v_pk_mul_f32 v[160:161], v[28:29], s[34:35]
	v_pk_mul_f32 v[162:163], v[30:31], s[34:35]
	v_pk_mul_f32 v[164:165], v[24:25], s[34:35]
	v_pk_mul_f32 v[166:167], v[26:27], s[34:35]
	v_exp_f32_e32 v160, v160
	v_exp_f32_e32 v161, v161
	v_exp_f32_e32 v162, v162
	v_exp_f32_e32 v163, v163
	v_exp_f32_e32 v164, v164
	v_exp_f32_e32 v165, v165
	v_exp_f32_e32 v166, v166
	v_exp_f32_e32 v167, v167
	v_pk_add_f32 v[160:161], v[160:161], 1.0 op_sel_hi:[1,0]
	v_pk_add_f32 v[162:163], v[162:163], 1.0 op_sel_hi:[1,0]
	v_pk_add_f32 v[164:165], v[164:165], 1.0 op_sel_hi:[1,0]
	v_pk_add_f32 v[166:167], v[166:167], 1.0 op_sel_hi:[1,0]
	v_rcp_f32_e32 v160, v160
	v_rcp_f32_e32 v161, v161
	v_rcp_f32_e32 v162, v162
	v_rcp_f32_e32 v163, v163
	v_rcp_f32_e32 v164, v164
	v_rcp_f32_e32 v165, v165
	v_rcp_f32_e32 v166, v166
	v_rcp_f32_e32 v167, v167
	v_pk_mul_f32 v[28:29], v[28:29], v[160:161]
	v_pk_mul_f32 v[30:31], v[30:31], v[162:163]
	v_pk_mul_f32 v[24:25], v[24:25], v[164:165]
	v_pk_mul_f32 v[26:27], v[26:27], v[166:167]
	v_pk_mul_f32 v[20:21], v[28:29], v[20:21]
	v_pk_mul_f32 v[22:23], v[30:31], v[22:23]
	v_pk_mul_f32 v[16:17], v[24:25], v[16:17]
	v_pk_mul_f32 v[18:19], v[26:27], v[18:19]
	v_add_u32_e32 v152, 0xa0, v144
	v_mad_i64_i32 v[150:151], s[30:31], v152, s23, v[138:139]
	v_cvt_pk_bf16_f32 v168, v20, v21
	v_cvt_pk_bf16_f32 v169, v22, v23
	v_cvt_pk_bf16_f32 v170, v16, v17
	v_cvt_pk_bf16_f32 v171, v18, v19
	v_lshl_add_u64 v[150:151], v[150:151], 0, v[148:149]
	global_store_dwordx4 v[150:151], v[168:171], off
	v_pk_mul_f32 v[160:161], v[12:13], s[34:35]
	v_pk_mul_f32 v[162:163], v[14:15], s[34:35]
	v_pk_mul_f32 v[164:165], v[8:9], s[34:35]
	v_pk_mul_f32 v[166:167], v[10:11], s[34:35]
	v_exp_f32_e32 v160, v160
	v_exp_f32_e32 v161, v161
	v_exp_f32_e32 v162, v162
	v_exp_f32_e32 v163, v163
	v_exp_f32_e32 v164, v164
	v_exp_f32_e32 v165, v165
	v_exp_f32_e32 v166, v166
	v_exp_f32_e32 v167, v167
	v_pk_add_f32 v[160:161], v[160:161], 1.0 op_sel_hi:[1,0]
	v_pk_add_f32 v[162:163], v[162:163], 1.0 op_sel_hi:[1,0]
	v_pk_add_f32 v[164:165], v[164:165], 1.0 op_sel_hi:[1,0]
	v_pk_add_f32 v[166:167], v[166:167], 1.0 op_sel_hi:[1,0]
	v_rcp_f32_e32 v160, v160
	v_rcp_f32_e32 v161, v161
	v_rcp_f32_e32 v162, v162
	v_rcp_f32_e32 v163, v163
	v_rcp_f32_e32 v164, v164
	v_rcp_f32_e32 v165, v165
	v_rcp_f32_e32 v166, v166
	v_rcp_f32_e32 v167, v167
	v_pk_mul_f32 v[12:13], v[12:13], v[160:161]
	v_pk_mul_f32 v[14:15], v[14:15], v[162:163]
	v_pk_mul_f32 v[8:9], v[8:9], v[164:165]
	v_pk_mul_f32 v[10:11], v[10:11], v[166:167]
	v_pk_mul_f32 v[4:5], v[12:13], v[4:5]
	v_pk_mul_f32 v[6:7], v[14:15], v[6:7]
	v_pk_mul_f32 v[0:1], v[8:9], v[0:1]
	v_pk_mul_f32 v[2:3], v[10:11], v[2:3]
	v_add_u32_e32 v152, 0xb0, v144
	v_mad_i64_i32 v[154:155], s[30:31], v152, s23, v[138:139]
	v_cvt_pk_bf16_f32 v172, v4, v5
	v_cvt_pk_bf16_f32 v173, v6, v7
	v_cvt_pk_bf16_f32 v174, v0, v1
	v_cvt_pk_bf16_f32 v175, v2, v3
	v_lshl_add_u64 v[154:155], v[154:155], 0, v[148:149]
	global_store_dwordx4 v[154:155], v[172:175], off
	s_andn2_b64 vcc, exec, s[4:5]
	s_mov_b64 s[4:5], -1
	s_cbranch_vccnz .LBB0_570
	s_andn2_b64 vcc, exec, s[12:13]
	s_cbranch_vccnz .LBB0_569
	s_barrier
	s_branch .LBB0_569
